# P1 tail half-unit: dedicated K-loop with two barriers per K-tile, unused A half not staged or read
# speedup vs baseline: 1.0058x; 1.0058x over previous
.LBB0_104:
	s_ashr_i32 s65, s64, 31
	s_lshl_b64 s[2:3], s[64:65], 19
	s_add_u32 s2, s80, s2
	s_addc_u32 s3, s81, s3
	s_cmp_gt_i32 s42, 0
	s_cselect_b32 s4, 0x40000, 0
	s_add_u32 s68, s2, s4
	s_addc_u32 s69, s3, 0
	s_and_b64 s[2:3], s[66:67], exec
	s_cselect_b32 s4, s69, s77
	s_cselect_b32 s43, s68, s76
	s_ashr_i32 s63, s62, 31
	s_lshl_b64 s[2:3], s[62:63], 19
	s_add_u32 s70, s10, s2
	s_addc_u32 s71, s11, s3
	s_and_b64 s[2:3], s[66:67], exec
	s_cselect_b32 s63, s71, s1
	s_cselect_b32 s65, s70, s0
	s_cmp_lt_i32 s33, 0
	v_mov_b32_e32 v4, v2
	v_mov_b32_e32 v5, v2
	s_cselect_b64 s[86:87], -1, 0
	s_add_u32 s36, s0, 0x100
	v_mov_b32_e32 v3, v2
	v_mov_b32_e32 v86, 0
	v_mov_b64_e32 v[24:25], v[4:5]
	v_mov_b64_e32 v[56:57], v[4:5]
	v_mov_b64_e32 v[28:29], v[4:5]
	v_mov_b64_e32 v[60:61], v[4:5]
	v_mov_b64_e32 v[36:37], v[4:5]
	v_mov_b64_e32 v[68:69], v[4:5]
	v_mov_b64_e32 v[32:33], v[4:5]
	v_mov_b64_e32 v[64:65], v[4:5]
	v_mov_b64_e32 v[12:13], v[4:5]
	v_mov_b64_e32 v[44:45], v[4:5]
	v_mov_b64_e32 v[16:17], v[4:5]
	v_mov_b64_e32 v[48:49], v[4:5]
	v_mov_b64_e32 v[20:21], v[4:5]
	v_mov_b64_e32 v[52:53], v[4:5]
	v_mov_b64_e32 v[8:9], v[4:5]
	v_mov_b64_e32 v[40:41], v[4:5]
	s_addc_u32 s44, s1, 0
	s_mov_b32 s45, -2
	v_mov_b64_e32 v[22:23], v[2:3]
	v_mov_b64_e32 v[54:55], v[2:3]
	v_mov_b64_e32 v[26:27], v[2:3]
	v_mov_b64_e32 v[58:59], v[2:3]
	v_mov_b64_e32 v[34:35], v[2:3]
	v_mov_b64_e32 v[66:67], v[2:3]
	v_mov_b64_e32 v[30:31], v[2:3]
	v_mov_b64_e32 v[62:63], v[2:3]
	v_mov_b64_e32 v[10:11], v[2:3]
	v_mov_b64_e32 v[42:43], v[2:3]
	v_mov_b64_e32 v[14:15], v[2:3]
	v_mov_b64_e32 v[46:47], v[2:3]
	v_mov_b64_e32 v[18:19], v[2:3]
	v_mov_b64_e32 v[50:51], v[2:3]
	v_mov_b64_e32 v[6:7], v[2:3]
	v_mov_b64_e32 v[38:39], v[2:3]
	v_mov_b32_e32 v87, v86
	v_mov_b32_e32 v88, v86
	v_mov_b32_e32 v89, v86
	v_mov_b32_e32 v118, v86
	v_mov_b32_e32 v119, v86
	v_mov_b32_e32 v120, v86
	v_mov_b32_e32 v121, v86
	v_mov_b32_e32 v90, v86
	v_mov_b32_e32 v91, v86
	v_mov_b32_e32 v92, v86
	v_mov_b32_e32 v93, v86
	v_mov_b32_e32 v122, v86
	v_mov_b32_e32 v123, v86
	v_mov_b32_e32 v124, v86
	v_mov_b32_e32 v125, v86
	v_mov_b32_e32 v94, v86
	v_mov_b32_e32 v95, v86
	v_mov_b32_e32 v96, v86
	v_mov_b32_e32 v97, v86
	v_mov_b32_e32 v126, v86
	v_mov_b32_e32 v127, v86
	v_mov_b32_e32 v128, v86
	v_mov_b32_e32 v129, v86
	v_mov_b32_e32 v98, v86
	v_mov_b32_e32 v99, v86
	v_mov_b32_e32 v100, v86
	v_mov_b32_e32 v101, v86
	v_mov_b32_e32 v130, v86
	v_mov_b32_e32 v131, v86
	v_mov_b32_e32 v132, v86
	v_mov_b32_e32 v133, v86
	v_mov_b32_e32 v74, v86
	v_mov_b32_e32 v75, v86
	v_mov_b32_e32 v76, v86
	v_mov_b32_e32 v77, v86
	v_mov_b32_e32 v106, v86
	v_mov_b32_e32 v107, v86
	v_mov_b32_e32 v108, v86
	v_mov_b32_e32 v109, v86
	v_mov_b32_e32 v78, v86
	v_mov_b32_e32 v79, v86
	v_mov_b32_e32 v80, v86
	v_mov_b32_e32 v81, v86
	v_mov_b32_e32 v110, v86
	v_mov_b32_e32 v111, v86
	v_mov_b32_e32 v112, v86
	v_mov_b32_e32 v113, v86
	v_mov_b32_e32 v82, v86
	v_mov_b32_e32 v83, v86
	v_mov_b32_e32 v84, v86
	v_mov_b32_e32 v85, v86
	v_mov_b32_e32 v114, v86
	v_mov_b32_e32 v115, v86
	v_mov_b32_e32 v116, v86
	v_mov_b32_e32 v117, v86
	v_mov_b32_e32 v70, v86
	v_mov_b32_e32 v71, v86
	v_mov_b32_e32 v72, v86
	v_mov_b32_e32 v73, v86
	v_mov_b32_e32 v102, v86
	v_mov_b32_e32 v103, v86
	v_mov_b32_e32 v104, v86
	v_mov_b32_e32 v105, v86
	s_and_b64 vcc, exec, s[86:87]
	s_cbranch_vccnz .LBB0_107
	s_add_u32 s2, s0, 0x100
	s_addc_u32 s3, s1, 0
	s_add_u32 s84, s76, 0x100
	s_addc_u32 s85, s77, 0
	s_mov_b32 s45, 0
.Lhu_loop:
	ds_read_b128 v[150:153], v248
	ds_read_b128 v[154:157], v248 offset:1024
	ds_read_b128 v[158:161], v248 offset:2048
	ds_read_b128 v[162:165], v248 offset:3072
	ds_read_b128 v[134:137], v249
	ds_read_b128 v[138:141], v249 offset:1024
	ds_read_b128 v[142:145], v249 offset:2048
	ds_read_b128 v[146:149], v249 offset:3072
	ds_read_b128 v[166:169], v250
	ds_read_b128 v[170:173], v250 offset:1024
	ds_read_b128 v[174:177], v250 offset:2048
	ds_read_b128 v[178:181], v250 offset:3072
	ds_read_b128 v[182:185], v250 offset:4096
	ds_read_b128 v[186:189], v250 offset:5120
	ds_read_b128 v[190:193], v250 offset:6144
	ds_read_b128 v[194:197], v250 offset:7168
	s_and_b64 vcc, exec, s[14:15]
	s_cbranch_vccz .Lhu_e_y
	s_cmp_eq_u32 s45, 0
	s_cbranch_scc1 .Lhu_e_bar
	v_lshl_add_u64 v[6:7], s[2:3], 0, v[208:209]
	v_lshl_add_u64 v[8:9], s[2:3], 0, v[212:213]
	s_add_u32 s88, s2, 0x40000
	s_addc_u32 s89, s3, 0
	v_lshl_add_u64 v[10:11], s[88:89], 0, v[208:209]
	v_lshl_add_u64 v[12:13], s[88:89], 0, v[212:213]
	v_lshl_add_u64 v[14:15], s[84:85], 0, v[206:207]
	v_lshl_add_u64 v[16:17], s[84:85], 0, v[210:211]
	s_add_u32 s2, s2, 0x80
	s_addc_u32 s3, s3, 0
	s_add_u32 s84, s84, 0x80
	s_addc_u32 s85, s85, 0
	s_mov_b32 m0, s54
	s_nop 0
	global_load_lds_dwordx4 v[6:7], off
	s_mov_b32 m0, s55
	s_nop 0
	global_load_lds_dwordx4 v[8:9], off
	s_mov_b32 m0, s59
	s_nop 0
	global_load_lds_dwordx4 v[10:11], off
	s_mov_b32 m0, s24
	s_nop 0
	global_load_lds_dwordx4 v[12:13], off
	s_mov_b32 m0, s57
	s_nop 0
	global_load_lds_dwordx4 v[14:15], off
	s_mov_b32 m0, s58
	s_nop 0
	global_load_lds_dwordx4 v[16:17], off
	s_branch .Lhu_e_bar

.Lhu_e_bar:
	s_waitcnt lgkmcnt(0)
	s_barrier
	s_and_b64 vcc, exec, s[14:15]
	s_cbranch_vccnz .Lhu_ec_x
	s_cmp_eq_u32 s45, 14
	s_cbranch_scc1 .Lhu_ec_ym
	v_lshl_add_u64 v[6:7], s[2:3], 0, v[208:209]
	v_lshl_add_u64 v[8:9], s[2:3], 0, v[212:213]
	s_add_u32 s88, s2, 0x40000
	s_addc_u32 s89, s3, 0
	v_lshl_add_u64 v[10:11], s[88:89], 0, v[208:209]
	v_lshl_add_u64 v[12:13], s[88:89], 0, v[212:213]
	v_lshl_add_u64 v[14:15], s[84:85], 0, v[206:207]
	v_lshl_add_u64 v[16:17], s[84:85], 0, v[210:211]
	s_add_u32 s2, s2, 0x80
	s_addc_u32 s3, s3, 0
	s_add_u32 s84, s84, 0x80
	s_addc_u32 s85, s85, 0
	s_mov_b32 m0, s73
	s_nop 0
	global_load_lds_dwordx4 v[6:7], off
	s_mov_b32 m0, s75
	s_nop 0
	global_load_lds_dwordx4 v[8:9], off
	s_mov_b32 m0, s92
	s_nop 0
	global_load_lds_dwordx4 v[10:11], off
	s_mov_b32 m0, s93
	s_nop 0
	global_load_lds_dwordx4 v[12:13], off
	s_mov_b32 m0, s61
	s_nop 0
	global_load_lds_dwordx4 v[14:15], off
	s_mov_b32 m0, s94
	s_nop 0
	global_load_lds_dwordx4 v[16:17], off
.Lhu_ec_ym:
	s_setprio 1
	v_mfma_f32_16x16x32_bf16 v[102:105], v[150:153], v[166:169], v[102:105]
	v_mfma_f32_16x16x32_bf16 v[70:73], v[158:161], v[166:169], v[70:73]
	v_mfma_f32_16x16x32_bf16 v[114:117], v[150:153], v[174:177], v[114:117]
	v_mfma_f32_16x16x32_bf16 v[82:85], v[158:161], v[174:177], v[82:85]
	v_mfma_f32_16x16x32_bf16 v[110:113], v[150:153], v[182:185], v[110:113]
	v_mfma_f32_16x16x32_bf16 v[78:81], v[158:161], v[182:185], v[78:81]
	v_mfma_f32_16x16x32_bf16 v[106:109], v[150:153], v[190:193], v[106:109]
	v_mfma_f32_16x16x32_bf16 v[74:77], v[158:161], v[190:193], v[74:77]
	v_mfma_f32_16x16x32_bf16 v[102:105], v[154:157], v[170:173], v[102:105]
	v_mfma_f32_16x16x32_bf16 v[70:73], v[162:165], v[170:173], v[70:73]
	v_mfma_f32_16x16x32_bf16 v[114:117], v[154:157], v[178:181], v[114:117]
	v_mfma_f32_16x16x32_bf16 v[82:85], v[162:165], v[178:181], v[82:85]
	v_mfma_f32_16x16x32_bf16 v[110:113], v[154:157], v[186:189], v[110:113]
	v_mfma_f32_16x16x32_bf16 v[78:81], v[162:165], v[186:189], v[78:81]
	v_mfma_f32_16x16x32_bf16 v[106:109], v[154:157], v[194:197], v[106:109]
	v_mfma_f32_16x16x32_bf16 v[74:77], v[162:165], v[194:197], v[74:77]
	s_setprio 0
	s_setprio 1
	v_mfma_f32_16x16x32_bf16 v[130:133], v[134:137], v[166:169], v[130:133]
	v_mfma_f32_16x16x32_bf16 v[98:101], v[142:145], v[166:169], v[98:101]
	v_mfma_f32_16x16x32_bf16 v[126:129], v[134:137], v[174:177], v[126:129]
	v_mfma_f32_16x16x32_bf16 v[94:97], v[142:145], v[174:177], v[94:97]
	v_mfma_f32_16x16x32_bf16 v[122:125], v[134:137], v[182:185], v[122:125]
	v_mfma_f32_16x16x32_bf16 v[90:93], v[142:145], v[182:185], v[90:93]
	v_mfma_f32_16x16x32_bf16 v[118:121], v[134:137], v[190:193], v[118:121]
	v_mfma_f32_16x16x32_bf16 v[86:89], v[142:145], v[190:193], v[86:89]
	v_mfma_f32_16x16x32_bf16 v[130:133], v[138:141], v[170:173], v[130:133]
	v_mfma_f32_16x16x32_bf16 v[98:101], v[146:149], v[170:173], v[98:101]
	v_mfma_f32_16x16x32_bf16 v[126:129], v[138:141], v[178:181], v[126:129]
	v_mfma_f32_16x16x32_bf16 v[94:97], v[146:149], v[178:181], v[94:97]
	v_mfma_f32_16x16x32_bf16 v[122:125], v[138:141], v[186:189], v[122:125]
	v_mfma_f32_16x16x32_bf16 v[90:93], v[146:149], v[186:189], v[90:93]
	v_mfma_f32_16x16x32_bf16 v[118:121], v[138:141], v[194:197], v[118:121]
	v_mfma_f32_16x16x32_bf16 v[86:89], v[146:149], v[194:197], v[86:89]
	s_setprio 0
	s_branch .Lhu_ec_cb
.Lhu_ec_x:
	s_setprio 1
	v_mfma_f32_16x16x32_bf16 v[102:105], v[150:153], v[166:169], v[102:105]
	v_mfma_f32_16x16x32_bf16 v[70:73], v[158:161], v[166:169], v[70:73]
	v_mfma_f32_16x16x32_bf16 v[114:117], v[150:153], v[174:177], v[114:117]
	v_mfma_f32_16x16x32_bf16 v[82:85], v[158:161], v[174:177], v[82:85]
	v_mfma_f32_16x16x32_bf16 v[110:113], v[150:153], v[182:185], v[110:113]
	v_mfma_f32_16x16x32_bf16 v[78:81], v[158:161], v[182:185], v[78:81]
	v_mfma_f32_16x16x32_bf16 v[106:109], v[150:153], v[190:193], v[106:109]
	v_mfma_f32_16x16x32_bf16 v[74:77], v[158:161], v[190:193], v[74:77]
	v_mfma_f32_16x16x32_bf16 v[102:105], v[154:157], v[170:173], v[102:105]
	v_mfma_f32_16x16x32_bf16 v[70:73], v[162:165], v[170:173], v[70:73]
	v_mfma_f32_16x16x32_bf16 v[114:117], v[154:157], v[178:181], v[114:117]
	v_mfma_f32_16x16x32_bf16 v[82:85], v[162:165], v[178:181], v[82:85]
	v_mfma_f32_16x16x32_bf16 v[110:113], v[154:157], v[186:189], v[110:113]
	v_mfma_f32_16x16x32_bf16 v[78:81], v[162:165], v[186:189], v[78:81]
	v_mfma_f32_16x16x32_bf16 v[106:109], v[154:157], v[194:197], v[106:109]
	v_mfma_f32_16x16x32_bf16 v[74:77], v[162:165], v[194:197], v[74:77]
	s_setprio 0
	s_setprio 1
	v_mfma_f32_16x16x32_bf16 v[130:133], v[134:137], v[166:169], v[130:133]
	v_mfma_f32_16x16x32_bf16 v[98:101], v[142:145], v[166:169], v[98:101]
	v_mfma_f32_16x16x32_bf16 v[126:129], v[134:137], v[174:177], v[126:129]
	v_mfma_f32_16x16x32_bf16 v[94:97], v[142:145], v[174:177], v[94:97]
	v_mfma_f32_16x16x32_bf16 v[122:125], v[134:137], v[182:185], v[122:125]
	v_mfma_f32_16x16x32_bf16 v[90:93], v[142:145], v[182:185], v[90:93]
	v_mfma_f32_16x16x32_bf16 v[118:121], v[134:137], v[190:193], v[118:121]
	v_mfma_f32_16x16x32_bf16 v[86:89], v[142:145], v[190:193], v[86:89]
	v_mfma_f32_16x16x32_bf16 v[130:133], v[138:141], v[170:173], v[130:133]
	v_mfma_f32_16x16x32_bf16 v[98:101], v[146:149], v[170:173], v[98:101]
	v_mfma_f32_16x16x32_bf16 v[126:129], v[138:141], v[178:181], v[126:129]
	v_mfma_f32_16x16x32_bf16 v[94:97], v[146:149], v[178:181], v[94:97]
	v_mfma_f32_16x16x32_bf16 v[122:125], v[138:141], v[186:189], v[122:125]
	v_mfma_f32_16x16x32_bf16 v[90:93], v[146:149], v[186:189], v[90:93]
	v_mfma_f32_16x16x32_bf16 v[118:121], v[138:141], v[194:197], v[118:121]
	v_mfma_f32_16x16x32_bf16 v[86:89], v[146:149], v[194:197], v[86:89]
	s_setprio 0
	s_waitcnt vmcnt(0)
.Lhu_ec_cb:
	s_barrier
	v_add_u32_e32 v3, 0x18000, v247
	v_add_u32_e32 v4, 0x1c000, v247
	ds_read_b128 v[150:153], v3
	ds_read_b128 v[154:157], v3 offset:1024
	ds_read_b128 v[158:161], v3 offset:2048
	ds_read_b128 v[162:165], v3 offset:3072
	ds_read_b128 v[134:137], v4
	ds_read_b128 v[138:141], v4 offset:1024
	ds_read_b128 v[142:145], v4 offset:2048
	ds_read_b128 v[146:149], v4 offset:3072
	ds_read_b128 v[190:193], v250 offset:32768
	ds_read_b128 v[194:197], v250 offset:33792
	ds_read_b128 v[182:185], v250 offset:34816
	ds_read_b128 v[186:189], v250 offset:35840
	ds_read_b128 v[174:177], v250 offset:36864
	ds_read_b128 v[178:181], v250 offset:37888
	ds_read_b128 v[166:169], v250 offset:38912
	ds_read_b128 v[170:173], v250 offset:39936
	s_and_b64 vcc, exec, s[14:15]
	s_cbranch_vccz .Lhu_o_y
	s_cmp_eq_u32 s45, 14
	s_cbranch_scc1 .Lhu_o_bar
	v_lshl_add_u64 v[6:7], s[2:3], 0, v[208:209]
	v_lshl_add_u64 v[8:9], s[2:3], 0, v[212:213]
	s_add_u32 s88, s2, 0x40000
	s_addc_u32 s89, s3, 0
	v_lshl_add_u64 v[10:11], s[88:89], 0, v[208:209]
	v_lshl_add_u64 v[12:13], s[88:89], 0, v[212:213]
	v_lshl_add_u64 v[14:15], s[84:85], 0, v[206:207]
	v_lshl_add_u64 v[16:17], s[84:85], 0, v[210:211]
	s_add_u32 s2, s2, 0x80
	s_addc_u32 s3, s3, 0
	s_add_u32 s84, s84, 0x80
	s_addc_u32 s85, s85, 0
	s_mov_b32 m0, s73
	s_nop 0
	global_load_lds_dwordx4 v[6:7], off
	s_mov_b32 m0, s75
	s_nop 0
	global_load_lds_dwordx4 v[8:9], off
	s_mov_b32 m0, s92
	s_nop 0
	global_load_lds_dwordx4 v[10:11], off
	s_mov_b32 m0, s93
	s_nop 0
	global_load_lds_dwordx4 v[12:13], off
	s_mov_b32 m0, s61
	s_nop 0
	global_load_lds_dwordx4 v[14:15], off
	s_mov_b32 m0, s94
	s_nop 0
	global_load_lds_dwordx4 v[16:17], off
	s_branch .Lhu_o_bar

.Lhu_o_bar:
	s_waitcnt lgkmcnt(0)
	s_barrier
	s_and_b64 vcc, exec, s[14:15]
	s_cbranch_vccnz .Lhu_oc_x
	s_cmp_eq_u32 s45, 14
	s_cbranch_scc1 .Lhu_oc_ym
	v_lshl_add_u64 v[6:7], s[2:3], 0, v[208:209]
	v_lshl_add_u64 v[8:9], s[2:3], 0, v[212:213]
	s_add_u32 s88, s2, 0x40000
	s_addc_u32 s89, s3, 0
	v_lshl_add_u64 v[10:11], s[88:89], 0, v[208:209]
	v_lshl_add_u64 v[12:13], s[88:89], 0, v[212:213]
	v_lshl_add_u64 v[14:15], s[84:85], 0, v[206:207]
	v_lshl_add_u64 v[16:17], s[84:85], 0, v[210:211]
	s_add_u32 s2, s2, 0x80
	s_addc_u32 s3, s3, 0
	s_add_u32 s84, s84, 0x80
	s_addc_u32 s85, s85, 0
	s_mov_b32 m0, s54
	s_nop 0
	global_load_lds_dwordx4 v[6:7], off
	s_mov_b32 m0, s55
	s_nop 0
	global_load_lds_dwordx4 v[8:9], off
	s_mov_b32 m0, s59
	s_nop 0
	global_load_lds_dwordx4 v[10:11], off
	s_mov_b32 m0, s24
	s_nop 0
	global_load_lds_dwordx4 v[12:13], off
	s_mov_b32 m0, s57
	s_nop 0
	global_load_lds_dwordx4 v[14:15], off
	s_mov_b32 m0, s58
	s_nop 0
	global_load_lds_dwordx4 v[16:17], off
.Lhu_oc_ym:
	s_setprio 1
	v_mfma_f32_16x16x32_bf16 v[102:105], v[150:153], v[190:193], v[102:105]
	v_mfma_f32_16x16x32_bf16 v[70:73], v[158:161], v[190:193], v[70:73]
	v_mfma_f32_16x16x32_bf16 v[114:117], v[150:153], v[182:185], v[114:117]
	v_mfma_f32_16x16x32_bf16 v[82:85], v[158:161], v[182:185], v[82:85]
	v_mfma_f32_16x16x32_bf16 v[110:113], v[150:153], v[174:177], v[110:113]
	v_mfma_f32_16x16x32_bf16 v[78:81], v[158:161], v[174:177], v[78:81]
	v_mfma_f32_16x16x32_bf16 v[106:109], v[150:153], v[166:169], v[106:109]
	v_mfma_f32_16x16x32_bf16 v[74:77], v[158:161], v[166:169], v[74:77]
	v_mfma_f32_16x16x32_bf16 v[102:105], v[154:157], v[194:197], v[102:105]
	v_mfma_f32_16x16x32_bf16 v[70:73], v[162:165], v[194:197], v[70:73]
	v_mfma_f32_16x16x32_bf16 v[114:117], v[154:157], v[186:189], v[114:117]
	v_mfma_f32_16x16x32_bf16 v[82:85], v[162:165], v[186:189], v[82:85]
	v_mfma_f32_16x16x32_bf16 v[110:113], v[154:157], v[178:181], v[110:113]
	v_mfma_f32_16x16x32_bf16 v[78:81], v[162:165], v[178:181], v[78:81]
	v_mfma_f32_16x16x32_bf16 v[106:109], v[154:157], v[170:173], v[106:109]
	v_mfma_f32_16x16x32_bf16 v[74:77], v[162:165], v[170:173], v[74:77]
	s_setprio 0
	s_setprio 1
	v_mfma_f32_16x16x32_bf16 v[130:133], v[134:137], v[190:193], v[130:133]
	v_mfma_f32_16x16x32_bf16 v[98:101], v[142:145], v[190:193], v[98:101]
	v_mfma_f32_16x16x32_bf16 v[126:129], v[134:137], v[182:185], v[126:129]
	v_mfma_f32_16x16x32_bf16 v[94:97], v[142:145], v[182:185], v[94:97]
	v_mfma_f32_16x16x32_bf16 v[122:125], v[134:137], v[174:177], v[122:125]
	v_mfma_f32_16x16x32_bf16 v[90:93], v[142:145], v[174:177], v[90:93]
	v_mfma_f32_16x16x32_bf16 v[118:121], v[134:137], v[166:169], v[118:121]
	v_mfma_f32_16x16x32_bf16 v[86:89], v[142:145], v[166:169], v[86:89]
	v_mfma_f32_16x16x32_bf16 v[130:133], v[138:141], v[194:197], v[130:133]
	v_mfma_f32_16x16x32_bf16 v[98:101], v[146:149], v[194:197], v[98:101]
	v_mfma_f32_16x16x32_bf16 v[126:129], v[138:141], v[186:189], v[126:129]
	v_mfma_f32_16x16x32_bf16 v[94:97], v[146:149], v[186:189], v[94:97]
	v_mfma_f32_16x16x32_bf16 v[122:125], v[138:141], v[178:181], v[122:125]
	v_mfma_f32_16x16x32_bf16 v[90:93], v[146:149], v[178:181], v[90:93]
	v_mfma_f32_16x16x32_bf16 v[118:121], v[138:141], v[170:173], v[118:121]
	v_mfma_f32_16x16x32_bf16 v[86:89], v[146:149], v[170:173], v[86:89]
	s_setprio 0
	s_branch .Lhu_oc_cb
.Lhu_oc_x:
	s_setprio 1
	v_mfma_f32_16x16x32_bf16 v[102:105], v[150:153], v[190:193], v[102:105]
	v_mfma_f32_16x16x32_bf16 v[70:73], v[158:161], v[190:193], v[70:73]
	v_mfma_f32_16x16x32_bf16 v[114:117], v[150:153], v[182:185], v[114:117]
	v_mfma_f32_16x16x32_bf16 v[82:85], v[158:161], v[182:185], v[82:85]
	v_mfma_f32_16x16x32_bf16 v[110:113], v[150:153], v[174:177], v[110:113]
	v_mfma_f32_16x16x32_bf16 v[78:81], v[158:161], v[174:177], v[78:81]
	v_mfma_f32_16x16x32_bf16 v[106:109], v[150:153], v[166:169], v[106:109]
	v_mfma_f32_16x16x32_bf16 v[74:77], v[158:161], v[166:169], v[74:77]
	v_mfma_f32_16x16x32_bf16 v[102:105], v[154:157], v[194:197], v[102:105]
	v_mfma_f32_16x16x32_bf16 v[70:73], v[162:165], v[194:197], v[70:73]
	v_mfma_f32_16x16x32_bf16 v[114:117], v[154:157], v[186:189], v[114:117]
	v_mfma_f32_16x16x32_bf16 v[82:85], v[162:165], v[186:189], v[82:85]
	v_mfma_f32_16x16x32_bf16 v[110:113], v[154:157], v[178:181], v[110:113]
	v_mfma_f32_16x16x32_bf16 v[78:81], v[162:165], v[178:181], v[78:81]
	v_mfma_f32_16x16x32_bf16 v[106:109], v[154:157], v[170:173], v[106:109]
	v_mfma_f32_16x16x32_bf16 v[74:77], v[162:165], v[170:173], v[74:77]
	s_setprio 0
	s_setprio 1
	v_mfma_f32_16x16x32_bf16 v[130:133], v[134:137], v[190:193], v[130:133]
	v_mfma_f32_16x16x32_bf16 v[98:101], v[142:145], v[190:193], v[98:101]
	v_mfma_f32_16x16x32_bf16 v[126:129], v[134:137], v[182:185], v[126:129]
	v_mfma_f32_16x16x32_bf16 v[94:97], v[142:145], v[182:185], v[94:97]
	v_mfma_f32_16x16x32_bf16 v[122:125], v[134:137], v[174:177], v[122:125]
	v_mfma_f32_16x16x32_bf16 v[90:93], v[142:145], v[174:177], v[90:93]
	v_mfma_f32_16x16x32_bf16 v[118:121], v[134:137], v[166:169], v[118:121]
	v_mfma_f32_16x16x32_bf16 v[86:89], v[142:145], v[166:169], v[86:89]
	v_mfma_f32_16x16x32_bf16 v[130:133], v[138:141], v[194:197], v[130:133]
	v_mfma_f32_16x16x32_bf16 v[98:101], v[146:149], v[194:197], v[98:101]
	v_mfma_f32_16x16x32_bf16 v[126:129], v[138:141], v[186:189], v[126:129]
	v_mfma_f32_16x16x32_bf16 v[94:97], v[146:149], v[186:189], v[94:97]
	v_mfma_f32_16x16x32_bf16 v[122:125], v[138:141], v[178:181], v[122:125]
	v_mfma_f32_16x16x32_bf16 v[90:93], v[146:149], v[178:181], v[90:93]
	v_mfma_f32_16x16x32_bf16 v[118:121], v[138:141], v[170:173], v[118:121]
	v_mfma_f32_16x16x32_bf16 v[86:89], v[146:149], v[170:173], v[86:89]
	s_setprio 0
	s_waitcnt vmcnt(0)
.Lhu_oc_cb:
	s_barrier
	s_add_i32 s45, s45, 2
	s_cmp_lt_u32 s45, 16
	s_cbranch_scc1 .Lhu_loop
	s_mov_b64 s[0:1], -1
	s_branch .LBB0_122
